# up-proj epilogue: conv predecessors for rows 0,1 of non-first 16-row groups via DPP row_ror from previous accumulators (f32); phase_fix skips those groups
# baseline (speedup 1.0000x reference)
.LBB0_387:
	s_or_b64 exec, exec, s[0:1]
	s_mov_b64 exec, s[74:75]
	v_add_u32_e32 v112, s6, v112
	s_mov_b32 s0, 0x58aff
	v_cmp_lt_i32_e32 vcc, s0, v112
	s_or_b64 s[52:53], vcc, s[52:53]
	v_add_u32_e32 v118, s13, v118
	s_andn2_b64 exec, exec, s[52:53]
	s_cbranch_execz .LBB0_399
.LBB0_388:
	s_mov_b32 s0, 0x2e8ba2e9
	v_mul_hi_i32 v0, v112, s0
	v_lshrrev_b32_e32 v1, 31, v0
	v_ashrrev_i32_e32 v0, 6, v0
	v_add_u32_e32 v119, v0, v1
	s_mov_b64 s[74:75], exec
	v_and_b32_e32 v124, 3, v119
	v_cmp_ne_u32_e64 s[76:77], 0, v124
	v_lshlrev_b32_e32 v124, 4, v119
	v_and_b32_e32 v124, 0x1ff0, v124
	v_cmp_ne_u32_e32 vcc, 0x1ff0, v124
	s_and_b64 s[76:77], s[76:77], vcc
	v_cmp_gt_i32_e32 vcc, 0x58000, v112
	s_and_b64 s[76:77], s[76:77], vcc
	s_andn2_b64 exec, exec, s[76:77]
	v_mul_i32_i24_e32 v0, 0x160, v119
	v_lshlrev_b32_e32 v0, 3, v0
	v_sub_u32_e32 v114, v118, v0
	v_ashrrev_i32_e32 v115, 31, v114
	v_lshlrev_b64 v[12:13], 2, v[114:115]
	v_lshl_add_u64 v[0:1], s[18:19], 0, v[12:13]
	global_load_dwordx4 v[16:19], v[0:1], off offset:16
	global_load_dwordx4 v[72:75], v[0:1], off
	v_lshl_add_u64 v[0:1], s[34:35], 0, v[12:13]
	global_load_dwordx4 v[20:23], v[0:1], off offset:16
	global_load_dwordx4 v[68:71], v[0:1], off
	v_lshl_add_u64 v[0:1], s[42:43], 0, v[12:13]
	global_load_dwordx4 v[24:27], v[0:1], off offset:16
	global_load_dwordx4 v[64:67], v[0:1], off
	v_lshl_add_u64 v[0:1], s[20:21], 0, v[12:13]
	v_lshl_add_u64 v[4:5], s[44:45], 0, v[12:13]
	v_lshl_add_u64 v[8:9], s[46:47], 0, v[12:13]
	v_lshl_add_u64 v[14:15], s[48:49], 0, v[12:13]
	v_lshl_add_u64 v[44:45], s[50:51], 0, v[12:13]
	global_load_dwordx4 v[28:31], v[0:1], off offset:16
	global_load_dwordx4 v[76:79], v[0:1], off
	s_nop 0
	global_load_dwordx4 v[0:3], v[4:5], off offset:16
	global_load_dwordx4 v[36:39], v[4:5], off
	s_nop 0
	global_load_dwordx4 v[4:7], v[8:9], off offset:16
	global_load_dwordx4 v[40:43], v[8:9], off
	s_nop 0
	global_load_dwordx4 v[8:11], v[14:15], off offset:16
	global_load_dwordx4 v[32:35], v[14:15], off
	s_nop 0
	global_load_dwordx4 v[12:15], v[44:45], off offset:16
	global_load_dwordx4 v[52:55], v[44:45], off
	v_lshlrev_b32_e32 v121, 4, v119
	s_mov_b32 s0, 0x57fff
	v_cmp_lt_i32_e64 s[40:41], s0, v112
	s_mov_b32 s0, 0x58000
	v_and_b32_e32 v120, 0x1ff0, v121
	v_cmp_gt_i32_e64 s[38:39], s0, v112
	v_cmp_ne_u32_e32 vcc, 0, v120
	s_and_b64 s[0:1], s[38:39], vcc
	s_and_saveexec_b64 s[4:5], s[0:1]
	s_xor_b64 s[0:1], exec, s[4:5]
	s_cbranch_execz .LBB0_390
	v_lshl_add_u32 v46, v119, 2, -2
	v_mov_b64_e32 v[44:45], s[10:11]
	s_movk_i32 s4, 0x2c00
	v_mad_i64_i32 v[44:45], s[4:5], v46, s4, v[44:45]
	v_lshl_add_u64 v[48:49], v[114:115], 1, v[44:45]
	v_add_co_u32_e32 v50, vcc, 0x2000, v48
	global_load_dwordx4 v[44:47], v[48:49], off
	s_nop 0
	v_addc_co_u32_e32 v51, vcc, 0, v49, vcc
	global_load_dwordx4 v[56:59], v[50:51], off offset:3072
	v_add_co_u32_e32 v50, vcc, s25, v48
	s_waitcnt vmcnt(0)
	v_lshlrev_b32_e32 v88, 16, v56
	v_addc_co_u32_e32 v51, vcc, 0, v49, vcc
	global_load_dwordx4 v[60:63], v[50:51], off offset:1536
	v_add_co_u32_e32 v48, vcc, s33, v48
	v_lshlrev_b32_e32 v84, 16, v44
	s_nop 0
	v_addc_co_u32_e32 v49, vcc, 0, v49, vcc
	global_load_dwordx4 v[96:99], v[48:49], off offset:512
	v_and_b32_e32 v85, 0xffff0000, v44
	v_lshlrev_b32_e32 v86, 16, v45
	v_and_b32_e32 v87, 0xffff0000, v45
	v_lshlrev_b32_e32 v48, 16, v46
	v_and_b32_e32 v49, 0xffff0000, v46
	v_lshlrev_b32_e32 v50, 16, v47
	v_and_b32_e32 v51, 0xffff0000, v47
	v_and_b32_e32 v89, 0xffff0000, v56
	v_lshlrev_b32_e32 v90, 16, v57
	v_and_b32_e32 v91, 0xffff0000, v57
	v_lshlrev_b32_e32 v44, 16, v58
	v_and_b32_e32 v45, 0xffff0000, v58
	v_lshlrev_b32_e32 v46, 16, v59
	v_and_b32_e32 v47, 0xffff0000, v59
	s_waitcnt vmcnt(1)
	v_lshlrev_b32_e32 v92, 16, v60
	v_and_b32_e32 v93, 0xffff0000, v60
	v_lshlrev_b32_e32 v94, 16, v61
	v_and_b32_e32 v95, 0xffff0000, v61
	v_lshlrev_b32_e32 v56, 16, v62
	v_and_b32_e32 v57, 0xffff0000, v62
	v_lshlrev_b32_e32 v58, 16, v63
	v_and_b32_e32 v59, 0xffff0000, v63
	s_waitcnt vmcnt(0)
	v_lshlrev_b32_e32 v80, 16, v96
	v_and_b32_e32 v81, 0xffff0000, v96
	v_lshlrev_b32_e32 v82, 16, v97
	v_and_b32_e32 v83, 0xffff0000, v97
	v_lshlrev_b32_e32 v60, 16, v98
	v_and_b32_e32 v61, 0xffff0000, v98
	v_lshlrev_b32_e32 v62, 16, v99
	v_and_b32_e32 v63, 0xffff0000, v99

.LBB0_605:
	s_or_b64 exec, exec, s[0:1]
	s_cmp_lg_u32 s42, 64
	s_cselect_b64 exec, -1, 0
	s_nop 1
	v_mov_b32_dpp v198, v68 row_ror:2 row_mask:0xf bank_mask:0x1
	v_mov_b32_dpp v196, v68 row_ror:1 row_mask:0xf bank_mask:0x1
	v_mov_b32_dpp v194, v126 row_ror:2 row_mask:0xf bank_mask:0x1
	v_mov_b32_dpp v192, v126 row_ror:1 row_mask:0xf bank_mask:0x1
	v_mov_b32_dpp v199, v69 row_ror:2 row_mask:0xf bank_mask:0x1
	v_mov_b32_dpp v197, v69 row_ror:1 row_mask:0xf bank_mask:0x1
	v_mov_b32_dpp v195, v127 row_ror:2 row_mask:0xf bank_mask:0x1
	v_mov_b32_dpp v193, v127 row_ror:1 row_mask:0xf bank_mask:0x1
	v_mov_b32_dpp v190, v70 row_ror:2 row_mask:0xf bank_mask:0x1
	v_mov_b32_dpp v188, v70 row_ror:1 row_mask:0xf bank_mask:0x1
	v_mov_b32_dpp v186, v128 row_ror:2 row_mask:0xf bank_mask:0x1
	v_mov_b32_dpp v184, v128 row_ror:1 row_mask:0xf bank_mask:0x1
	v_mov_b32_dpp v191, v71 row_ror:2 row_mask:0xf bank_mask:0x1
	v_mov_b32_dpp v189, v71 row_ror:1 row_mask:0xf bank_mask:0x1
	v_mov_b32_dpp v187, v129 row_ror:2 row_mask:0xf bank_mask:0x1
	v_mov_b32_dpp v185, v129 row_ror:1 row_mask:0xf bank_mask:0x1
	s_mov_b64 exec, -1
	s_nop 1
	v_mov_b32_dpp v198, v52 row_shr:2 row_mask:0xf bank_mask:0xf
	v_mov_b32_dpp v196, v52 row_shr:1 row_mask:0xf bank_mask:0xf
	v_mov_b32_dpp v194, v118 row_shr:2 row_mask:0xf bank_mask:0xf
	v_mov_b32_dpp v192, v118 row_shr:1 row_mask:0xf bank_mask:0xf
	v_mov_b32_dpp v199, v53 row_shr:2 row_mask:0xf bank_mask:0xf
	v_mov_b32_dpp v197, v53 row_shr:1 row_mask:0xf bank_mask:0xf
	v_mov_b32_dpp v195, v119 row_shr:2 row_mask:0xf bank_mask:0xf
	v_mov_b32_dpp v193, v119 row_shr:1 row_mask:0xf bank_mask:0xf
	v_mov_b32_dpp v190, v54 row_shr:2 row_mask:0xf bank_mask:0xf
	v_mov_b32_dpp v188, v54 row_shr:1 row_mask:0xf bank_mask:0xf
	v_mov_b32_dpp v186, v120 row_shr:2 row_mask:0xf bank_mask:0xf
	v_mov_b32_dpp v184, v120 row_shr:1 row_mask:0xf bank_mask:0xf
	v_mov_b32_dpp v191, v55 row_shr:2 row_mask:0xf bank_mask:0xf
	v_mov_b32_dpp v189, v55 row_shr:1 row_mask:0xf bank_mask:0xf
	v_mov_b32_dpp v187, v121 row_shr:2 row_mask:0xf bank_mask:0xf
	v_mov_b32_dpp v185, v121 row_shr:1 row_mask:0xf bank_mask:0xf
	v_or_b32_e32 v175, 16, v172
	s_cmp_lg_u32 s42, 64
	s_cselect_b64 vcc, -1, s[40:41]
	s_and_saveexec_b64 s[0:1], vcc
	s_cbranch_execz .LBB0_607
	s_nop 0
	v_pk_fma_f32 v[198:199], v[146:147], v[198:199], v[158:159]
	v_pk_fma_f32 v[190:191], v[148:149], v[190:191], v[160:161]
	v_pk_fma_f32 v[196:197], v[150:151], v[196:197], v[198:199]
	v_pk_fma_f32 v[188:189], v[152:153], v[188:189], v[190:191]
	v_pk_fma_f32 v[196:197], v[52:53], v[154:155], v[196:197]
	v_pk_fma_f32 v[188:189], v[54:55], v[156:157], v[188:189]
	v_mul_f32_e32 v173, 0x3dd2d3e8, v196
	v_fmaak_f32 v173, v196, v173, 0x40135761
	v_mul_f32_e32 v198, 0x3dd2d3e8, v197
	v_mul_f32_e32 v173, v196, v173
	v_fmaak_f32 v198, v197, v198, 0x40135761
	v_exp_f32_e32 v173, v173
	v_mul_f32_e32 v198, v197, v198
	v_exp_f32_e32 v199, v198
	v_mul_f32_e32 v190, 0x3dd2d3e8, v189
	v_add_f32_e32 v173, 1.0, v173
	v_rcp_f32_e32 v198, v173
	v_add_f32_e32 v173, 1.0, v199
	v_rcp_f32_e32 v199, v173
	v_mul_f32_e32 v173, 0x3dd2d3e8, v188
	v_fmaak_f32 v173, v188, v173, 0x40135761
	v_mul_f32_e32 v173, v188, v173
	v_fmaak_f32 v190, v189, v190, 0x40135761
	v_pk_fma_f32 v[194:195], v[130:131], v[194:195], v[142:143]
	v_exp_f32_e32 v173, v173
	v_mul_f32_e32 v190, v189, v190
	v_pk_fma_f32 v[192:193], v[134:135], v[192:193], v[194:195]
	v_pk_fma_f32 v[194:195], v[196:197], v[198:199], v[196:197] neg_lo:[1,0,0] neg_hi:[1,0,0]
	v_exp_f32_e32 v196, v190
	v_pk_fma_f32 v[192:193], v[118:119], v[138:139], v[192:193]
	v_add_f32_e32 v173, 1.0, v173
	v_pk_mul_f32 v[190:191], v[192:193], v[194:195]
	v_rcp_f32_e32 v192, v173
	v_add_f32_e32 v173, 1.0, v196
	v_rcp_f32_e32 v193, v173
	v_pk_fma_f32 v[186:187], v[132:133], v[186:187], v[144:145]
	s_nop 0
	v_pk_fma_f32 v[184:185], v[136:137], v[184:185], v[186:187]
	v_pk_fma_f32 v[186:187], v[188:189], v[192:193], v[188:189] neg_lo:[1,0,0] neg_hi:[1,0,0]
	v_pk_fma_f32 v[184:185], v[120:121], v[140:141], v[184:185]
	s_nop 0
	v_pk_mul_f32 v[184:185], v[184:185], v[186:187]
	v_cvt_pk_bf16_f32 v186, v190, v191
	v_cvt_pk_bf16_f32 v187, v184, v185
	v_mad_i64_i32 v[184:185], s[6:7], v175, s5, v[178:179]
	global_store_dwordx2 v[184:185], v[186:187], off
.LBB0_607:
	s_or_b64 exec, exec, s[0:1]
	s_cmp_lg_u32 s42, 64
	s_cselect_b64 exec, -1, 0
	s_nop 1
	v_mov_b32_dpp v198, v52 row_ror:2 row_mask:0xf bank_mask:0x1
	v_mov_b32_dpp v196, v52 row_ror:1 row_mask:0xf bank_mask:0x1
	v_mov_b32_dpp v194, v118 row_ror:2 row_mask:0xf bank_mask:0x1
	v_mov_b32_dpp v192, v118 row_ror:1 row_mask:0xf bank_mask:0x1
	v_mov_b32_dpp v199, v53 row_ror:2 row_mask:0xf bank_mask:0x1
	v_mov_b32_dpp v197, v53 row_ror:1 row_mask:0xf bank_mask:0x1
	v_mov_b32_dpp v195, v119 row_ror:2 row_mask:0xf bank_mask:0x1
	v_mov_b32_dpp v193, v119 row_ror:1 row_mask:0xf bank_mask:0x1
	v_mov_b32_dpp v190, v54 row_ror:2 row_mask:0xf bank_mask:0x1
	v_mov_b32_dpp v188, v54 row_ror:1 row_mask:0xf bank_mask:0x1
	v_mov_b32_dpp v186, v120 row_ror:2 row_mask:0xf bank_mask:0x1
	v_mov_b32_dpp v184, v120 row_ror:1 row_mask:0xf bank_mask:0x1
	v_mov_b32_dpp v191, v55 row_ror:2 row_mask:0xf bank_mask:0x1
	v_mov_b32_dpp v189, v55 row_ror:1 row_mask:0xf bank_mask:0x1
	v_mov_b32_dpp v187, v121 row_ror:2 row_mask:0xf bank_mask:0x1
	v_mov_b32_dpp v185, v121 row_ror:1 row_mask:0xf bank_mask:0x1
	s_mov_b64 exec, -1
	s_nop 1
	v_mov_b32_dpp v198, v44 row_shr:2 row_mask:0xf bank_mask:0xf
	v_mov_b32_dpp v196, v44 row_shr:1 row_mask:0xf bank_mask:0xf
	v_mov_b32_dpp v194, v108 row_shr:2 row_mask:0xf bank_mask:0xf
	v_mov_b32_dpp v192, v108 row_shr:1 row_mask:0xf bank_mask:0xf
	v_mov_b32_dpp v199, v45 row_shr:2 row_mask:0xf bank_mask:0xf
	v_mov_b32_dpp v197, v45 row_shr:1 row_mask:0xf bank_mask:0xf
	v_mov_b32_dpp v195, v109 row_shr:2 row_mask:0xf bank_mask:0xf
	v_mov_b32_dpp v193, v109 row_shr:1 row_mask:0xf bank_mask:0xf
	v_mov_b32_dpp v190, v46 row_shr:2 row_mask:0xf bank_mask:0xf
	v_mov_b32_dpp v188, v46 row_shr:1 row_mask:0xf bank_mask:0xf
	v_mov_b32_dpp v186, v110 row_shr:2 row_mask:0xf bank_mask:0xf
	v_mov_b32_dpp v184, v110 row_shr:1 row_mask:0xf bank_mask:0xf
	v_mov_b32_dpp v191, v47 row_shr:2 row_mask:0xf bank_mask:0xf
	v_mov_b32_dpp v189, v47 row_shr:1 row_mask:0xf bank_mask:0xf
	v_mov_b32_dpp v187, v111 row_shr:2 row_mask:0xf bank_mask:0xf
	v_mov_b32_dpp v185, v111 row_shr:1 row_mask:0xf bank_mask:0xf
	v_or_b32_e32 v205, 32, v172
	s_cmp_lg_u32 s42, 64
	s_cselect_b64 vcc, -1, s[40:41]
	s_and_saveexec_b64 s[0:1], vcc
	s_cbranch_execz .LBB0_609
	s_nop 0
	v_pk_fma_f32 v[198:199], v[146:147], v[198:199], v[158:159]
	v_pk_fma_f32 v[190:191], v[148:149], v[190:191], v[160:161]
	v_pk_fma_f32 v[196:197], v[150:151], v[196:197], v[198:199]
	v_pk_fma_f32 v[188:189], v[152:153], v[188:189], v[190:191]
	v_pk_fma_f32 v[196:197], v[44:45], v[154:155], v[196:197]
	v_pk_fma_f32 v[188:189], v[46:47], v[156:157], v[188:189]
	v_mul_f32_e32 v173, 0x3dd2d3e8, v196
	v_fmaak_f32 v173, v196, v173, 0x40135761
	v_mul_f32_e32 v198, 0x3dd2d3e8, v197
	v_mul_f32_e32 v173, v196, v173
	v_fmaak_f32 v198, v197, v198, 0x40135761
	v_exp_f32_e32 v173, v173
	v_mul_f32_e32 v198, v197, v198
	v_exp_f32_e32 v199, v198
	v_mul_f32_e32 v190, 0x3dd2d3e8, v189
	v_add_f32_e32 v173, 1.0, v173
	v_rcp_f32_e32 v198, v173
	v_add_f32_e32 v173, 1.0, v199
	v_rcp_f32_e32 v199, v173
	v_mul_f32_e32 v173, 0x3dd2d3e8, v188
	v_fmaak_f32 v173, v188, v173, 0x40135761
	v_mul_f32_e32 v173, v188, v173
	v_fmaak_f32 v190, v189, v190, 0x40135761
	v_pk_fma_f32 v[194:195], v[130:131], v[194:195], v[142:143]
	v_exp_f32_e32 v173, v173
	v_mul_f32_e32 v190, v189, v190
	v_pk_fma_f32 v[192:193], v[134:135], v[192:193], v[194:195]
	v_pk_fma_f32 v[194:195], v[196:197], v[198:199], v[196:197] neg_lo:[1,0,0] neg_hi:[1,0,0]
	v_exp_f32_e32 v196, v190
	v_pk_fma_f32 v[192:193], v[108:109], v[138:139], v[192:193]
	v_add_f32_e32 v173, 1.0, v173
	v_pk_mul_f32 v[190:191], v[192:193], v[194:195]
	v_rcp_f32_e32 v192, v173
	v_add_f32_e32 v173, 1.0, v196
	v_rcp_f32_e32 v193, v173
	v_pk_fma_f32 v[186:187], v[132:133], v[186:187], v[144:145]
	s_nop 0
	v_pk_fma_f32 v[184:185], v[136:137], v[184:185], v[186:187]
	v_pk_fma_f32 v[186:187], v[188:189], v[192:193], v[188:189] neg_lo:[1,0,0] neg_hi:[1,0,0]
	v_pk_fma_f32 v[184:185], v[110:111], v[140:141], v[184:185]
	s_nop 0
	v_pk_mul_f32 v[184:185], v[184:185], v[186:187]
	v_cvt_pk_bf16_f32 v186, v190, v191
	v_cvt_pk_bf16_f32 v187, v184, v185
	v_mad_i64_i32 v[184:185], s[6:7], v205, s5, v[178:179]
	global_store_dwordx2 v[184:185], v[186:187], off
.LBB0_609:
	s_or_b64 exec, exec, s[0:1]
	s_cmp_lg_u32 s42, 64
	s_cselect_b64 exec, -1, 0
	s_nop 1
	v_mov_b32_dpp v198, v44 row_ror:2 row_mask:0xf bank_mask:0x1
	v_mov_b32_dpp v196, v44 row_ror:1 row_mask:0xf bank_mask:0x1
	v_mov_b32_dpp v194, v108 row_ror:2 row_mask:0xf bank_mask:0x1
	v_mov_b32_dpp v192, v108 row_ror:1 row_mask:0xf bank_mask:0x1
	v_mov_b32_dpp v199, v45 row_ror:2 row_mask:0xf bank_mask:0x1
	v_mov_b32_dpp v197, v45 row_ror:1 row_mask:0xf bank_mask:0x1
	v_mov_b32_dpp v195, v109 row_ror:2 row_mask:0xf bank_mask:0x1
	v_mov_b32_dpp v193, v109 row_ror:1 row_mask:0xf bank_mask:0x1
	v_mov_b32_dpp v190, v46 row_ror:2 row_mask:0xf bank_mask:0x1
	v_mov_b32_dpp v188, v46 row_ror:1 row_mask:0xf bank_mask:0x1
	v_mov_b32_dpp v186, v110 row_ror:2 row_mask:0xf bank_mask:0x1
	v_mov_b32_dpp v184, v110 row_ror:1 row_mask:0xf bank_mask:0x1
	v_mov_b32_dpp v191, v47 row_ror:2 row_mask:0xf bank_mask:0x1
	v_mov_b32_dpp v189, v47 row_ror:1 row_mask:0xf bank_mask:0x1
	v_mov_b32_dpp v187, v111 row_ror:2 row_mask:0xf bank_mask:0x1
	v_mov_b32_dpp v185, v111 row_ror:1 row_mask:0xf bank_mask:0x1
	s_mov_b64 exec, -1
	s_nop 1
	v_mov_b32_dpp v198, v36 row_shr:2 row_mask:0xf bank_mask:0xf
	v_mov_b32_dpp v196, v36 row_shr:1 row_mask:0xf bank_mask:0xf
	v_mov_b32_dpp v194, v100 row_shr:2 row_mask:0xf bank_mask:0xf
	v_mov_b32_dpp v192, v100 row_shr:1 row_mask:0xf bank_mask:0xf
	v_mov_b32_dpp v199, v37 row_shr:2 row_mask:0xf bank_mask:0xf
	v_mov_b32_dpp v197, v37 row_shr:1 row_mask:0xf bank_mask:0xf
	v_mov_b32_dpp v195, v101 row_shr:2 row_mask:0xf bank_mask:0xf
	v_mov_b32_dpp v193, v101 row_shr:1 row_mask:0xf bank_mask:0xf
	v_mov_b32_dpp v190, v38 row_shr:2 row_mask:0xf bank_mask:0xf
	v_mov_b32_dpp v188, v38 row_shr:1 row_mask:0xf bank_mask:0xf
	v_mov_b32_dpp v186, v102 row_shr:2 row_mask:0xf bank_mask:0xf
	v_mov_b32_dpp v184, v102 row_shr:1 row_mask:0xf bank_mask:0xf
	v_mov_b32_dpp v191, v39 row_shr:2 row_mask:0xf bank_mask:0xf
	v_mov_b32_dpp v189, v39 row_shr:1 row_mask:0xf bank_mask:0xf
	v_mov_b32_dpp v187, v103 row_shr:2 row_mask:0xf bank_mask:0xf
	v_mov_b32_dpp v185, v103 row_shr:1 row_mask:0xf bank_mask:0xf
	v_or_b32_e32 v206, 48, v172
	s_cmp_lg_u32 s42, 64
	s_cselect_b64 vcc, -1, s[40:41]
	s_and_saveexec_b64 s[0:1], vcc
	s_cbranch_execz .LBB0_611
	s_nop 0
	v_pk_fma_f32 v[198:199], v[146:147], v[198:199], v[158:159]
	v_pk_fma_f32 v[190:191], v[148:149], v[190:191], v[160:161]
	v_pk_fma_f32 v[196:197], v[150:151], v[196:197], v[198:199]
	v_pk_fma_f32 v[188:189], v[152:153], v[188:189], v[190:191]
	v_pk_fma_f32 v[196:197], v[36:37], v[154:155], v[196:197]
	v_pk_fma_f32 v[188:189], v[38:39], v[156:157], v[188:189]
	v_mul_f32_e32 v173, 0x3dd2d3e8, v196
	v_fmaak_f32 v173, v196, v173, 0x40135761
	v_mul_f32_e32 v198, 0x3dd2d3e8, v197
	v_mul_f32_e32 v173, v196, v173
	v_fmaak_f32 v198, v197, v198, 0x40135761
	v_exp_f32_e32 v173, v173
	v_mul_f32_e32 v198, v197, v198
	v_exp_f32_e32 v199, v198
	v_mul_f32_e32 v190, 0x3dd2d3e8, v189
	v_add_f32_e32 v173, 1.0, v173
	v_rcp_f32_e32 v198, v173
	v_add_f32_e32 v173, 1.0, v199
	v_rcp_f32_e32 v199, v173
	v_mul_f32_e32 v173, 0x3dd2d3e8, v188
	v_fmaak_f32 v173, v188, v173, 0x40135761
	v_mul_f32_e32 v173, v188, v173
	v_fmaak_f32 v190, v189, v190, 0x40135761
	v_pk_fma_f32 v[194:195], v[130:131], v[194:195], v[142:143]
	v_exp_f32_e32 v173, v173
	v_mul_f32_e32 v190, v189, v190
	v_pk_fma_f32 v[192:193], v[134:135], v[192:193], v[194:195]
	v_pk_fma_f32 v[194:195], v[196:197], v[198:199], v[196:197] neg_lo:[1,0,0] neg_hi:[1,0,0]
	v_exp_f32_e32 v196, v190
	v_pk_fma_f32 v[192:193], v[100:101], v[138:139], v[192:193]
	v_add_f32_e32 v173, 1.0, v173
	v_pk_mul_f32 v[190:191], v[192:193], v[194:195]
	v_rcp_f32_e32 v192, v173
	v_add_f32_e32 v173, 1.0, v196
	v_rcp_f32_e32 v193, v173
	v_pk_fma_f32 v[186:187], v[132:133], v[186:187], v[144:145]
	s_nop 0
	v_pk_fma_f32 v[184:185], v[136:137], v[184:185], v[186:187]
	v_pk_fma_f32 v[186:187], v[188:189], v[192:193], v[188:189] neg_lo:[1,0,0] neg_hi:[1,0,0]
	v_pk_fma_f32 v[184:185], v[102:103], v[140:141], v[184:185]
	s_nop 0
	v_pk_mul_f32 v[184:185], v[184:185], v[186:187]
	v_cvt_pk_bf16_f32 v186, v190, v191
	v_cvt_pk_bf16_f32 v187, v184, v185
	v_mad_i64_i32 v[184:185], s[6:7], v206, s5, v[178:179]
	global_store_dwordx2 v[184:185], v[186:187], off

.LBB0_613:
	s_or_b64 exec, exec, s[0:1]
	s_cmp_lg_u32 s42, 64
	s_cselect_b64 exec, -1, 0
	s_nop 1
	v_mov_b32_dpp v198, v28 row_ror:2 row_mask:0xf bank_mask:0x1
	v_mov_b32_dpp v196, v28 row_ror:1 row_mask:0xf bank_mask:0x1
	v_mov_b32_dpp v194, v92 row_ror:2 row_mask:0xf bank_mask:0x1
	v_mov_b32_dpp v192, v92 row_ror:1 row_mask:0xf bank_mask:0x1
	v_mov_b32_dpp v199, v29 row_ror:2 row_mask:0xf bank_mask:0x1
	v_mov_b32_dpp v197, v29 row_ror:1 row_mask:0xf bank_mask:0x1
	v_mov_b32_dpp v195, v93 row_ror:2 row_mask:0xf bank_mask:0x1
	v_mov_b32_dpp v193, v93 row_ror:1 row_mask:0xf bank_mask:0x1
	v_mov_b32_dpp v190, v30 row_ror:2 row_mask:0xf bank_mask:0x1
	v_mov_b32_dpp v188, v30 row_ror:1 row_mask:0xf bank_mask:0x1
	v_mov_b32_dpp v186, v94 row_ror:2 row_mask:0xf bank_mask:0x1
	v_mov_b32_dpp v184, v94 row_ror:1 row_mask:0xf bank_mask:0x1
	v_mov_b32_dpp v191, v31 row_ror:2 row_mask:0xf bank_mask:0x1
	v_mov_b32_dpp v189, v31 row_ror:1 row_mask:0xf bank_mask:0x1
	v_mov_b32_dpp v187, v95 row_ror:2 row_mask:0xf bank_mask:0x1
	v_mov_b32_dpp v185, v95 row_ror:1 row_mask:0xf bank_mask:0x1
	s_mov_b64 exec, -1
	s_nop 1
	v_mov_b32_dpp v198, v20 row_shr:2 row_mask:0xf bank_mask:0xf
	v_mov_b32_dpp v196, v20 row_shr:1 row_mask:0xf bank_mask:0xf
	v_mov_b32_dpp v194, v84 row_shr:2 row_mask:0xf bank_mask:0xf
	v_mov_b32_dpp v192, v84 row_shr:1 row_mask:0xf bank_mask:0xf
	v_mov_b32_dpp v199, v21 row_shr:2 row_mask:0xf bank_mask:0xf
	v_mov_b32_dpp v197, v21 row_shr:1 row_mask:0xf bank_mask:0xf
	v_mov_b32_dpp v195, v85 row_shr:2 row_mask:0xf bank_mask:0xf
	v_mov_b32_dpp v193, v85 row_shr:1 row_mask:0xf bank_mask:0xf
	v_mov_b32_dpp v190, v22 row_shr:2 row_mask:0xf bank_mask:0xf
	v_mov_b32_dpp v188, v22 row_shr:1 row_mask:0xf bank_mask:0xf
	v_mov_b32_dpp v186, v86 row_shr:2 row_mask:0xf bank_mask:0xf
	v_mov_b32_dpp v184, v86 row_shr:1 row_mask:0xf bank_mask:0xf
	v_mov_b32_dpp v191, v23 row_shr:2 row_mask:0xf bank_mask:0xf
	v_mov_b32_dpp v189, v23 row_shr:1 row_mask:0xf bank_mask:0xf
	v_mov_b32_dpp v187, v87 row_shr:2 row_mask:0xf bank_mask:0xf
	v_mov_b32_dpp v185, v87 row_shr:1 row_mask:0xf bank_mask:0xf
	v_add_u32_e32 v207, 0x90, v172
	s_cmp_lg_u32 s42, 64
	s_cselect_b64 vcc, -1, s[40:41]
	s_and_saveexec_b64 s[0:1], vcc
	s_cbranch_execz .LBB0_615
	s_nop 0
	v_pk_fma_f32 v[198:199], v[146:147], v[198:199], v[158:159]
	v_pk_fma_f32 v[190:191], v[148:149], v[190:191], v[160:161]
	v_pk_fma_f32 v[196:197], v[150:151], v[196:197], v[198:199]
	v_pk_fma_f32 v[188:189], v[152:153], v[188:189], v[190:191]
	v_pk_fma_f32 v[196:197], v[20:21], v[154:155], v[196:197]
	v_pk_fma_f32 v[188:189], v[22:23], v[156:157], v[188:189]
	v_mul_f32_e32 v198, 0x3dd2d3e8, v196
	v_mul_f32_e32 v199, 0x3dd2d3e8, v197
	v_fmaak_f32 v198, v196, v198, 0x40135761
	v_fmaak_f32 v199, v197, v199, 0x40135761
	v_mul_f32_e32 v198, v196, v198
	v_mul_f32_e32 v199, v197, v199
	v_exp_f32_e32 v198, v198
	v_exp_f32_e32 v199, v199
	v_mul_f32_e32 v190, 0x3dd2d3e8, v188
	v_fmaak_f32 v190, v188, v190, 0x40135761
	v_add_f32_e32 v198, 1.0, v198
	v_add_f32_e32 v199, 1.0, v199
	v_rcp_f32_e32 v198, v198
	v_rcp_f32_e32 v199, v199
	v_pk_fma_f32 v[194:195], v[130:131], v[194:195], v[142:143]
	v_mul_f32_e32 v190, v188, v190
	v_pk_fma_f32 v[192:193], v[134:135], v[192:193], v[194:195]
	v_pk_fma_f32 v[194:195], v[196:197], v[198:199], v[196:197] neg_lo:[1,0,0] neg_hi:[1,0,0]
	v_exp_f32_e32 v196, v190
	v_mul_f32_e32 v190, 0x3dd2d3e8, v189
	v_fmaak_f32 v190, v189, v190, 0x40135761
	v_mul_f32_e32 v190, v189, v190
	v_exp_f32_e32 v197, v190
	v_pk_fma_f32 v[192:193], v[84:85], v[138:139], v[192:193]
	v_pk_fma_f32 v[186:187], v[132:133], v[186:187], v[144:145]
	v_pk_mul_f32 v[190:191], v[192:193], v[194:195]
	v_add_f32_e32 v192, 1.0, v196
	v_add_f32_e32 v193, 1.0, v197
	v_rcp_f32_e32 v192, v192
	v_rcp_f32_e32 v193, v193
	v_pk_fma_f32 v[184:185], v[136:137], v[184:185], v[186:187]
	v_pk_fma_f32 v[186:187], v[188:189], v[192:193], v[188:189] neg_lo:[1,0,0] neg_hi:[1,0,0]
	v_pk_fma_f32 v[184:185], v[86:87], v[140:141], v[184:185]
	s_nop 0
	v_pk_mul_f32 v[184:185], v[184:185], v[186:187]
	v_cvt_pk_bf16_f32 v186, v190, v191
	v_cvt_pk_bf16_f32 v187, v184, v185
	v_mad_i64_i32 v[184:185], s[6:7], v207, s5, v[178:179]
	global_store_dwordx2 v[184:185], v[186:187], off
.LBB0_615:
	s_or_b64 exec, exec, s[0:1]
	s_cmp_lg_u32 s42, 64
	s_cselect_b64 exec, -1, 0
	s_nop 1
	v_mov_b32_dpp v198, v20 row_ror:2 row_mask:0xf bank_mask:0x1
	v_mov_b32_dpp v196, v20 row_ror:1 row_mask:0xf bank_mask:0x1
	v_mov_b32_dpp v194, v84 row_ror:2 row_mask:0xf bank_mask:0x1
	v_mov_b32_dpp v192, v84 row_ror:1 row_mask:0xf bank_mask:0x1
	v_mov_b32_dpp v199, v21 row_ror:2 row_mask:0xf bank_mask:0x1
	v_mov_b32_dpp v197, v21 row_ror:1 row_mask:0xf bank_mask:0x1
	v_mov_b32_dpp v195, v85 row_ror:2 row_mask:0xf bank_mask:0x1
	v_mov_b32_dpp v193, v85 row_ror:1 row_mask:0xf bank_mask:0x1
	v_mov_b32_dpp v190, v22 row_ror:2 row_mask:0xf bank_mask:0x1
	v_mov_b32_dpp v188, v22 row_ror:1 row_mask:0xf bank_mask:0x1
	v_mov_b32_dpp v186, v86 row_ror:2 row_mask:0xf bank_mask:0x1
	v_mov_b32_dpp v184, v86 row_ror:1 row_mask:0xf bank_mask:0x1
	v_mov_b32_dpp v191, v23 row_ror:2 row_mask:0xf bank_mask:0x1
	v_mov_b32_dpp v189, v23 row_ror:1 row_mask:0xf bank_mask:0x1
	v_mov_b32_dpp v187, v87 row_ror:2 row_mask:0xf bank_mask:0x1
	v_mov_b32_dpp v185, v87 row_ror:1 row_mask:0xf bank_mask:0x1
	s_mov_b64 exec, -1
	s_nop 1
	v_mov_b32_dpp v198, v12 row_shr:2 row_mask:0xf bank_mask:0xf
	v_mov_b32_dpp v196, v12 row_shr:1 row_mask:0xf bank_mask:0xf
	v_mov_b32_dpp v194, v76 row_shr:2 row_mask:0xf bank_mask:0xf
	v_mov_b32_dpp v192, v76 row_shr:1 row_mask:0xf bank_mask:0xf
	v_mov_b32_dpp v199, v13 row_shr:2 row_mask:0xf bank_mask:0xf
	v_mov_b32_dpp v197, v13 row_shr:1 row_mask:0xf bank_mask:0xf
	v_mov_b32_dpp v195, v77 row_shr:2 row_mask:0xf bank_mask:0xf
	v_mov_b32_dpp v193, v77 row_shr:1 row_mask:0xf bank_mask:0xf
	v_mov_b32_dpp v190, v14 row_shr:2 row_mask:0xf bank_mask:0xf
	v_mov_b32_dpp v188, v14 row_shr:1 row_mask:0xf bank_mask:0xf
	v_mov_b32_dpp v186, v78 row_shr:2 row_mask:0xf bank_mask:0xf
	v_mov_b32_dpp v184, v78 row_shr:1 row_mask:0xf bank_mask:0xf
	v_mov_b32_dpp v191, v15 row_shr:2 row_mask:0xf bank_mask:0xf
	v_mov_b32_dpp v189, v15 row_shr:1 row_mask:0xf bank_mask:0xf
	v_mov_b32_dpp v187, v79 row_shr:2 row_mask:0xf bank_mask:0xf
	v_mov_b32_dpp v185, v79 row_shr:1 row_mask:0xf bank_mask:0xf
	v_add_u32_e32 v208, 0xa0, v172
	s_cmp_lg_u32 s42, 64
	s_cselect_b64 vcc, -1, s[40:41]
	s_and_saveexec_b64 s[0:1], vcc
	s_cbranch_execz .LBB0_617
	s_nop 0
	v_pk_fma_f32 v[198:199], v[146:147], v[198:199], v[158:159]
	v_pk_fma_f32 v[190:191], v[148:149], v[190:191], v[160:161]
	v_pk_fma_f32 v[196:197], v[150:151], v[196:197], v[198:199]
	v_pk_fma_f32 v[188:189], v[152:153], v[188:189], v[190:191]
	v_pk_fma_f32 v[196:197], v[12:13], v[154:155], v[196:197]
	v_pk_fma_f32 v[188:189], v[14:15], v[156:157], v[188:189]
	v_mul_f32_e32 v198, 0x3dd2d3e8, v196
	v_mul_f32_e32 v199, 0x3dd2d3e8, v197
	v_fmaak_f32 v198, v196, v198, 0x40135761
	v_fmaak_f32 v199, v197, v199, 0x40135761
	v_mul_f32_e32 v198, v196, v198
	v_mul_f32_e32 v199, v197, v199
	v_exp_f32_e32 v198, v198
	v_exp_f32_e32 v199, v199
	v_mul_f32_e32 v190, 0x3dd2d3e8, v188
	v_fmaak_f32 v190, v188, v190, 0x40135761
	v_add_f32_e32 v198, 1.0, v198
	v_add_f32_e32 v199, 1.0, v199
	v_rcp_f32_e32 v198, v198
	v_rcp_f32_e32 v199, v199
	v_pk_fma_f32 v[194:195], v[130:131], v[194:195], v[142:143]
	v_mul_f32_e32 v190, v188, v190
	v_pk_fma_f32 v[192:193], v[134:135], v[192:193], v[194:195]
	v_pk_fma_f32 v[194:195], v[196:197], v[198:199], v[196:197] neg_lo:[1,0,0] neg_hi:[1,0,0]
	v_exp_f32_e32 v196, v190
	v_mul_f32_e32 v190, 0x3dd2d3e8, v189
	v_fmaak_f32 v190, v189, v190, 0x40135761
	v_mul_f32_e32 v190, v189, v190
	v_exp_f32_e32 v197, v190
	v_pk_fma_f32 v[192:193], v[76:77], v[138:139], v[192:193]
	v_pk_fma_f32 v[186:187], v[132:133], v[186:187], v[144:145]
	v_pk_mul_f32 v[190:191], v[192:193], v[194:195]
	v_add_f32_e32 v192, 1.0, v196
	v_add_f32_e32 v193, 1.0, v197
	v_rcp_f32_e32 v192, v192
	v_rcp_f32_e32 v193, v193
	v_pk_fma_f32 v[184:185], v[136:137], v[184:185], v[186:187]
	v_pk_fma_f32 v[186:187], v[188:189], v[192:193], v[188:189] neg_lo:[1,0,0] neg_hi:[1,0,0]
	v_pk_fma_f32 v[184:185], v[78:79], v[140:141], v[184:185]
	s_nop 0
	v_pk_mul_f32 v[184:185], v[184:185], v[186:187]
	v_cvt_pk_bf16_f32 v186, v190, v191
	v_cvt_pk_bf16_f32 v187, v184, v185
	v_mad_i64_i32 v[184:185], s[6:7], v208, s5, v[178:179]
	global_store_dwordx2 v[184:185], v[186:187], off
.LBB0_617:
	s_or_b64 exec, exec, s[0:1]
	s_cmp_lg_u32 s42, 64
	s_cselect_b64 exec, -1, 0
	s_nop 1
	v_mov_b32_dpp v198, v12 row_ror:2 row_mask:0xf bank_mask:0x1
	v_mov_b32_dpp v196, v12 row_ror:1 row_mask:0xf bank_mask:0x1
	v_mov_b32_dpp v194, v76 row_ror:2 row_mask:0xf bank_mask:0x1
	v_mov_b32_dpp v192, v76 row_ror:1 row_mask:0xf bank_mask:0x1
	v_mov_b32_dpp v199, v13 row_ror:2 row_mask:0xf bank_mask:0x1
	v_mov_b32_dpp v197, v13 row_ror:1 row_mask:0xf bank_mask:0x1
	v_mov_b32_dpp v195, v77 row_ror:2 row_mask:0xf bank_mask:0x1
	v_mov_b32_dpp v193, v77 row_ror:1 row_mask:0xf bank_mask:0x1
	v_mov_b32_dpp v190, v14 row_ror:2 row_mask:0xf bank_mask:0x1
	v_mov_b32_dpp v188, v14 row_ror:1 row_mask:0xf bank_mask:0x1
	v_mov_b32_dpp v186, v78 row_ror:2 row_mask:0xf bank_mask:0x1
	v_mov_b32_dpp v184, v78 row_ror:1 row_mask:0xf bank_mask:0x1
	v_mov_b32_dpp v191, v15 row_ror:2 row_mask:0xf bank_mask:0x1
	v_mov_b32_dpp v189, v15 row_ror:1 row_mask:0xf bank_mask:0x1
	v_mov_b32_dpp v187, v79 row_ror:2 row_mask:0xf bank_mask:0x1
	v_mov_b32_dpp v185, v79 row_ror:1 row_mask:0xf bank_mask:0x1
	s_mov_b64 exec, -1
	s_nop 1
	v_mov_b32_dpp v198, v4 row_shr:2 row_mask:0xf bank_mask:0xf
	v_mov_b32_dpp v196, v4 row_shr:1 row_mask:0xf bank_mask:0xf
	v_mov_b32_dpp v194, v64 row_shr:2 row_mask:0xf bank_mask:0xf
	v_mov_b32_dpp v192, v64 row_shr:1 row_mask:0xf bank_mask:0xf
	v_mov_b32_dpp v199, v5 row_shr:2 row_mask:0xf bank_mask:0xf
	v_mov_b32_dpp v197, v5 row_shr:1 row_mask:0xf bank_mask:0xf
	v_mov_b32_dpp v195, v65 row_shr:2 row_mask:0xf bank_mask:0xf
	v_mov_b32_dpp v193, v65 row_shr:1 row_mask:0xf bank_mask:0xf
	v_mov_b32_dpp v190, v6 row_shr:2 row_mask:0xf bank_mask:0xf
	v_mov_b32_dpp v188, v6 row_shr:1 row_mask:0xf bank_mask:0xf
	v_mov_b32_dpp v186, v66 row_shr:2 row_mask:0xf bank_mask:0xf
	v_mov_b32_dpp v184, v66 row_shr:1 row_mask:0xf bank_mask:0xf
	v_mov_b32_dpp v191, v7 row_shr:2 row_mask:0xf bank_mask:0xf
	v_mov_b32_dpp v189, v7 row_shr:1 row_mask:0xf bank_mask:0xf
	v_mov_b32_dpp v187, v67 row_shr:2 row_mask:0xf bank_mask:0xf
	v_mov_b32_dpp v185, v67 row_shr:1 row_mask:0xf bank_mask:0xf
	v_add_u32_e32 v209, 0xb0, v172
	s_cmp_lg_u32 s42, 64
	s_cselect_b64 vcc, -1, s[40:41]
	s_and_saveexec_b64 s[0:1], vcc
	s_cbranch_execz .LBB0_619
	s_nop 0
	v_pk_fma_f32 v[146:147], v[146:147], v[198:199], v[158:159]
	v_pk_fma_f32 v[130:131], v[130:131], v[194:195], v[142:143]
	v_pk_fma_f32 v[146:147], v[150:151], v[196:197], v[146:147]
	v_pk_fma_f32 v[130:131], v[134:135], v[192:193], v[130:131]
	v_pk_fma_f32 v[146:147], v[4:5], v[154:155], v[146:147]
	v_pk_fma_f32 v[130:131], v[64:65], v[138:139], v[130:131]
	v_mul_f32_e32 v150, 0x3dd2d3e8, v146
	v_mul_f32_e32 v151, 0x3dd2d3e8, v147
	v_fmaak_f32 v150, v146, v150, 0x40135761
	v_fmaak_f32 v151, v147, v151, 0x40135761
	v_mul_f32_e32 v150, v146, v150
	v_mul_f32_e32 v151, v147, v151
	v_exp_f32_e32 v150, v150
	v_exp_f32_e32 v151, v151
	v_pk_fma_f32 v[138:139], v[148:149], v[190:191], v[160:161]
	v_pk_fma_f32 v[132:133], v[132:133], v[186:187], v[144:145]
	v_pk_fma_f32 v[138:139], v[152:153], v[188:189], v[138:139]
	v_add_f32_e32 v150, 1.0, v150
	v_pk_fma_f32 v[138:139], v[6:7], v[156:157], v[138:139]
	v_add_f32_e32 v151, 1.0, v151
	v_mul_f32_e32 v142, 0x3dd2d3e8, v138
	v_mul_f32_e32 v143, 0x3dd2d3e8, v139
	v_fmaak_f32 v142, v138, v142, 0x40135761
	v_fmaak_f32 v143, v139, v143, 0x40135761
	v_rcp_f32_e32 v150, v150
	v_rcp_f32_e32 v151, v151
	v_mul_f32_e32 v142, v138, v142
	v_mul_f32_e32 v143, v139, v143
	v_exp_f32_e32 v142, v142
	v_exp_f32_e32 v143, v143
	v_pk_fma_f32 v[134:135], v[146:147], v[150:151], v[146:147] neg_lo:[1,0,0] neg_hi:[1,0,0]
	v_pk_fma_f32 v[132:133], v[136:137], v[184:185], v[132:133]
	v_pk_mul_f32 v[130:131], v[130:131], v[134:135]
	v_add_f32_e32 v134, 1.0, v142
	v_add_f32_e32 v135, 1.0, v143
	v_rcp_f32_e32 v134, v134
	v_rcp_f32_e32 v135, v135
	v_pk_fma_f32 v[132:133], v[66:67], v[140:141], v[132:133]
	v_cvt_pk_bf16_f32 v130, v130, v131
	v_pk_fma_f32 v[134:135], v[138:139], v[134:135], v[138:139] neg_lo:[1,0,0] neg_hi:[1,0,0]
	s_nop 0
	v_pk_mul_f32 v[132:133], v[132:133], v[134:135]
	s_nop 0
	v_cvt_pk_bf16_f32 v131, v132, v133
	v_mad_i64_i32 v[132:133], s[6:7], v209, s5, v[178:179]
	global_store_dwordx2 v[132:133], v[130:131], off

.LBB0_621:
	s_or_b64 exec, exec, s[0:1]
	s_cmp_lg_u32 s42, 64
	s_cselect_b64 exec, -1, 0
	s_nop 1
	v_mov_b32_dpp v194, v56 row_ror:2 row_mask:0xf bank_mask:0x1
	v_mov_b32_dpp v192, v56 row_ror:1 row_mask:0xf bank_mask:0x1
	v_mov_b32_dpp v190, v122 row_ror:2 row_mask:0xf bank_mask:0x1
	v_mov_b32_dpp v188, v122 row_ror:1 row_mask:0xf bank_mask:0x1
	v_mov_b32_dpp v195, v57 row_ror:2 row_mask:0xf bank_mask:0x1
	v_mov_b32_dpp v193, v57 row_ror:1 row_mask:0xf bank_mask:0x1
	v_mov_b32_dpp v191, v123 row_ror:2 row_mask:0xf bank_mask:0x1
	v_mov_b32_dpp v189, v123 row_ror:1 row_mask:0xf bank_mask:0x1
	v_mov_b32_dpp v186, v58 row_ror:2 row_mask:0xf bank_mask:0x1
	v_mov_b32_dpp v184, v58 row_ror:1 row_mask:0xf bank_mask:0x1
	v_mov_b32_dpp v182, v124 row_ror:2 row_mask:0xf bank_mask:0x1
	v_mov_b32_dpp v180, v124 row_ror:1 row_mask:0xf bank_mask:0x1
	v_mov_b32_dpp v187, v59 row_ror:2 row_mask:0xf bank_mask:0x1
	v_mov_b32_dpp v185, v59 row_ror:1 row_mask:0xf bank_mask:0x1
	v_mov_b32_dpp v183, v125 row_ror:2 row_mask:0xf bank_mask:0x1
	v_mov_b32_dpp v181, v125 row_ror:1 row_mask:0xf bank_mask:0x1
	s_mov_b64 exec, -1
	s_nop 1
	v_mov_b32_dpp v194, v48 row_shr:2 row_mask:0xf bank_mask:0xf
	v_mov_b32_dpp v192, v48 row_shr:1 row_mask:0xf bank_mask:0xf
	v_mov_b32_dpp v190, v114 row_shr:2 row_mask:0xf bank_mask:0xf
	v_mov_b32_dpp v188, v114 row_shr:1 row_mask:0xf bank_mask:0xf
	v_mov_b32_dpp v195, v49 row_shr:2 row_mask:0xf bank_mask:0xf
	v_mov_b32_dpp v193, v49 row_shr:1 row_mask:0xf bank_mask:0xf
	v_mov_b32_dpp v191, v115 row_shr:2 row_mask:0xf bank_mask:0xf
	v_mov_b32_dpp v189, v115 row_shr:1 row_mask:0xf bank_mask:0xf
	v_mov_b32_dpp v186, v50 row_shr:2 row_mask:0xf bank_mask:0xf
	v_mov_b32_dpp v184, v50 row_shr:1 row_mask:0xf bank_mask:0xf
	v_mov_b32_dpp v182, v116 row_shr:2 row_mask:0xf bank_mask:0xf
	v_mov_b32_dpp v180, v116 row_shr:1 row_mask:0xf bank_mask:0xf
	v_mov_b32_dpp v187, v51 row_shr:2 row_mask:0xf bank_mask:0xf
	v_mov_b32_dpp v185, v51 row_shr:1 row_mask:0xf bank_mask:0xf
	v_mov_b32_dpp v183, v117 row_shr:2 row_mask:0xf bank_mask:0xf
	v_mov_b32_dpp v181, v117 row_shr:1 row_mask:0xf bank_mask:0xf
	s_cmp_lg_u32 s42, 64
	s_cselect_b64 vcc, -1, s[40:41]
	s_and_saveexec_b64 s[0:1], vcc
	s_cbranch_execz .LBB0_623
	s_nop 0
	v_pk_fma_f32 v[194:195], v[146:147], v[194:195], v[158:159]
	v_pk_fma_f32 v[186:187], v[148:149], v[186:187], v[160:161]
	v_pk_fma_f32 v[192:193], v[150:151], v[192:193], v[194:195]
	v_pk_fma_f32 v[184:185], v[152:153], v[184:185], v[186:187]
	v_pk_fma_f32 v[192:193], v[48:49], v[154:155], v[192:193]
	v_pk_fma_f32 v[184:185], v[50:51], v[156:157], v[184:185]
	v_mul_f32_e32 v194, 0x3dd2d3e8, v192
	v_mul_f32_e32 v195, 0x3dd2d3e8, v193
	v_fmaak_f32 v194, v192, v194, 0x40135761
	v_fmaak_f32 v195, v193, v195, 0x40135761
	v_mul_f32_e32 v194, v192, v194
	v_mul_f32_e32 v195, v193, v195
	v_exp_f32_e32 v194, v194
	v_exp_f32_e32 v195, v195
	v_mul_f32_e32 v186, 0x3dd2d3e8, v184
	v_fmaak_f32 v186, v184, v186, 0x40135761
	v_add_f32_e32 v194, 1.0, v194
	v_add_f32_e32 v195, 1.0, v195
	v_rcp_f32_e32 v194, v194
	v_rcp_f32_e32 v195, v195
	s_nop 0
	v_pk_fma_f32 v[190:191], v[130:131], v[190:191], v[142:143]
	v_mul_f32_e32 v186, v184, v186
	v_pk_fma_f32 v[188:189], v[134:135], v[188:189], v[190:191]
	v_pk_fma_f32 v[190:191], v[192:193], v[194:195], v[192:193] neg_lo:[1,0,0] neg_hi:[1,0,0]
	v_exp_f32_e32 v192, v186
	v_mul_f32_e32 v186, 0x3dd2d3e8, v185
	v_fmaak_f32 v186, v185, v186, 0x40135761
	v_mul_f32_e32 v186, v185, v186
	v_exp_f32_e32 v193, v186
	v_pk_fma_f32 v[188:189], v[114:115], v[138:139], v[188:189]
	v_pk_fma_f32 v[182:183], v[132:133], v[182:183], v[144:145]
	v_pk_mul_f32 v[186:187], v[188:189], v[190:191]
	v_add_f32_e32 v188, 1.0, v192
	v_add_f32_e32 v189, 1.0, v193
	v_rcp_f32_e32 v188, v188
	v_rcp_f32_e32 v189, v189
	v_pk_fma_f32 v[180:181], v[136:137], v[180:181], v[182:183]
	v_pk_fma_f32 v[182:183], v[184:185], v[188:189], v[184:185] neg_lo:[1,0,0] neg_hi:[1,0,0]
	v_pk_fma_f32 v[180:181], v[116:117], v[140:141], v[180:181]
	s_nop 0
	v_pk_mul_f32 v[180:181], v[180:181], v[182:183]
	v_cvt_pk_bf16_f32 v182, v186, v187
	v_cvt_pk_bf16_f32 v183, v180, v181
	v_mad_i64_i32 v[180:181], s[6:7], v175, s5, v[178:179]
	global_store_dwordx2 v[180:181], v[182:183], off offset:8
.LBB0_623:
	s_or_b64 exec, exec, s[0:1]
	s_cmp_lg_u32 s42, 64
	s_cselect_b64 exec, -1, 0
	s_nop 1
	v_mov_b32_dpp v194, v48 row_ror:2 row_mask:0xf bank_mask:0x1
	v_mov_b32_dpp v192, v48 row_ror:1 row_mask:0xf bank_mask:0x1
	v_mov_b32_dpp v190, v114 row_ror:2 row_mask:0xf bank_mask:0x1
	v_mov_b32_dpp v188, v114 row_ror:1 row_mask:0xf bank_mask:0x1
	v_mov_b32_dpp v195, v49 row_ror:2 row_mask:0xf bank_mask:0x1
	v_mov_b32_dpp v193, v49 row_ror:1 row_mask:0xf bank_mask:0x1
	v_mov_b32_dpp v191, v115 row_ror:2 row_mask:0xf bank_mask:0x1
	v_mov_b32_dpp v189, v115 row_ror:1 row_mask:0xf bank_mask:0x1
	v_mov_b32_dpp v186, v50 row_ror:2 row_mask:0xf bank_mask:0x1
	v_mov_b32_dpp v184, v50 row_ror:1 row_mask:0xf bank_mask:0x1
	v_mov_b32_dpp v182, v116 row_ror:2 row_mask:0xf bank_mask:0x1
	v_mov_b32_dpp v180, v116 row_ror:1 row_mask:0xf bank_mask:0x1
	v_mov_b32_dpp v187, v51 row_ror:2 row_mask:0xf bank_mask:0x1
	v_mov_b32_dpp v185, v51 row_ror:1 row_mask:0xf bank_mask:0x1
	v_mov_b32_dpp v183, v117 row_ror:2 row_mask:0xf bank_mask:0x1
	v_mov_b32_dpp v181, v117 row_ror:1 row_mask:0xf bank_mask:0x1
	s_mov_b64 exec, -1
	s_nop 1
	v_mov_b32_dpp v194, v40 row_shr:2 row_mask:0xf bank_mask:0xf
	v_mov_b32_dpp v192, v40 row_shr:1 row_mask:0xf bank_mask:0xf
	v_mov_b32_dpp v190, v104 row_shr:2 row_mask:0xf bank_mask:0xf
	v_mov_b32_dpp v188, v104 row_shr:1 row_mask:0xf bank_mask:0xf
	v_mov_b32_dpp v195, v41 row_shr:2 row_mask:0xf bank_mask:0xf
	v_mov_b32_dpp v193, v41 row_shr:1 row_mask:0xf bank_mask:0xf
	v_mov_b32_dpp v191, v105 row_shr:2 row_mask:0xf bank_mask:0xf
	v_mov_b32_dpp v189, v105 row_shr:1 row_mask:0xf bank_mask:0xf
	v_mov_b32_dpp v186, v42 row_shr:2 row_mask:0xf bank_mask:0xf
	v_mov_b32_dpp v184, v42 row_shr:1 row_mask:0xf bank_mask:0xf
	v_mov_b32_dpp v182, v106 row_shr:2 row_mask:0xf bank_mask:0xf
	v_mov_b32_dpp v180, v106 row_shr:1 row_mask:0xf bank_mask:0xf
	v_mov_b32_dpp v187, v43 row_shr:2 row_mask:0xf bank_mask:0xf
	v_mov_b32_dpp v185, v43 row_shr:1 row_mask:0xf bank_mask:0xf
	v_mov_b32_dpp v183, v107 row_shr:2 row_mask:0xf bank_mask:0xf
	v_mov_b32_dpp v181, v107 row_shr:1 row_mask:0xf bank_mask:0xf
	s_cmp_lg_u32 s42, 64
	s_cselect_b64 vcc, -1, s[40:41]
	s_and_saveexec_b64 s[0:1], vcc
	s_cbranch_execz .LBB0_625
	s_nop 0
	v_pk_fma_f32 v[194:195], v[146:147], v[194:195], v[158:159]
	v_pk_fma_f32 v[186:187], v[148:149], v[186:187], v[160:161]
	v_pk_fma_f32 v[192:193], v[150:151], v[192:193], v[194:195]
	v_pk_fma_f32 v[184:185], v[152:153], v[184:185], v[186:187]
	v_pk_fma_f32 v[192:193], v[40:41], v[154:155], v[192:193]
	v_pk_fma_f32 v[184:185], v[42:43], v[156:157], v[184:185]
	v_mul_f32_e32 v175, 0x3dd2d3e8, v192
	v_fmaak_f32 v175, v192, v175, 0x40135761
	v_mul_f32_e32 v194, 0x3dd2d3e8, v193
	v_mul_f32_e32 v175, v192, v175
	v_fmaak_f32 v194, v193, v194, 0x40135761
	v_exp_f32_e32 v175, v175
	v_mul_f32_e32 v194, v193, v194
	v_exp_f32_e32 v195, v194
	v_mul_f32_e32 v186, 0x3dd2d3e8, v185
	v_add_f32_e32 v175, 1.0, v175
	v_rcp_f32_e32 v194, v175
	v_add_f32_e32 v175, 1.0, v195
	v_rcp_f32_e32 v195, v175
	v_mul_f32_e32 v175, 0x3dd2d3e8, v184
	v_fmaak_f32 v175, v184, v175, 0x40135761
	v_mul_f32_e32 v175, v184, v175
	v_fmaak_f32 v186, v185, v186, 0x40135761
	s_nop 0
	v_pk_fma_f32 v[190:191], v[130:131], v[190:191], v[142:143]
	v_exp_f32_e32 v175, v175
	v_mul_f32_e32 v186, v185, v186
	v_pk_fma_f32 v[188:189], v[134:135], v[188:189], v[190:191]
	v_pk_fma_f32 v[190:191], v[192:193], v[194:195], v[192:193] neg_lo:[1,0,0] neg_hi:[1,0,0]
	v_exp_f32_e32 v192, v186
	v_pk_fma_f32 v[188:189], v[104:105], v[138:139], v[188:189]
	v_add_f32_e32 v175, 1.0, v175
	v_pk_mul_f32 v[186:187], v[188:189], v[190:191]
	v_rcp_f32_e32 v188, v175
	v_add_f32_e32 v175, 1.0, v192
	v_rcp_f32_e32 v189, v175
	v_pk_fma_f32 v[182:183], v[132:133], v[182:183], v[144:145]
	s_nop 0
	v_pk_fma_f32 v[180:181], v[136:137], v[180:181], v[182:183]
	v_pk_fma_f32 v[182:183], v[184:185], v[188:189], v[184:185] neg_lo:[1,0,0] neg_hi:[1,0,0]
	v_pk_fma_f32 v[180:181], v[106:107], v[140:141], v[180:181]
	s_nop 0
	v_pk_mul_f32 v[180:181], v[180:181], v[182:183]
	v_cvt_pk_bf16_f32 v182, v186, v187
	v_cvt_pk_bf16_f32 v183, v180, v181
	v_mad_i64_i32 v[180:181], s[6:7], v205, s5, v[178:179]
	global_store_dwordx2 v[180:181], v[182:183], off offset:8
.LBB0_625:
	s_or_b64 exec, exec, s[0:1]
	s_cmp_lg_u32 s42, 64
	s_cselect_b64 exec, -1, 0
	s_nop 1
	v_mov_b32_dpp v194, v40 row_ror:2 row_mask:0xf bank_mask:0x1
	v_mov_b32_dpp v192, v40 row_ror:1 row_mask:0xf bank_mask:0x1
	v_mov_b32_dpp v190, v104 row_ror:2 row_mask:0xf bank_mask:0x1
	v_mov_b32_dpp v188, v104 row_ror:1 row_mask:0xf bank_mask:0x1
	v_mov_b32_dpp v195, v41 row_ror:2 row_mask:0xf bank_mask:0x1
	v_mov_b32_dpp v193, v41 row_ror:1 row_mask:0xf bank_mask:0x1
	v_mov_b32_dpp v191, v105 row_ror:2 row_mask:0xf bank_mask:0x1
	v_mov_b32_dpp v189, v105 row_ror:1 row_mask:0xf bank_mask:0x1
	v_mov_b32_dpp v186, v42 row_ror:2 row_mask:0xf bank_mask:0x1
	v_mov_b32_dpp v184, v42 row_ror:1 row_mask:0xf bank_mask:0x1
	v_mov_b32_dpp v182, v106 row_ror:2 row_mask:0xf bank_mask:0x1
	v_mov_b32_dpp v180, v106 row_ror:1 row_mask:0xf bank_mask:0x1
	v_mov_b32_dpp v187, v43 row_ror:2 row_mask:0xf bank_mask:0x1
	v_mov_b32_dpp v185, v43 row_ror:1 row_mask:0xf bank_mask:0x1
	v_mov_b32_dpp v183, v107 row_ror:2 row_mask:0xf bank_mask:0x1
	v_mov_b32_dpp v181, v107 row_ror:1 row_mask:0xf bank_mask:0x1
	s_mov_b64 exec, -1
	s_nop 1
	v_mov_b32_dpp v194, v32 row_shr:2 row_mask:0xf bank_mask:0xf
	v_mov_b32_dpp v192, v32 row_shr:1 row_mask:0xf bank_mask:0xf
	v_mov_b32_dpp v190, v96 row_shr:2 row_mask:0xf bank_mask:0xf
	v_mov_b32_dpp v188, v96 row_shr:1 row_mask:0xf bank_mask:0xf
	v_mov_b32_dpp v195, v33 row_shr:2 row_mask:0xf bank_mask:0xf
	v_mov_b32_dpp v193, v33 row_shr:1 row_mask:0xf bank_mask:0xf
	v_mov_b32_dpp v191, v97 row_shr:2 row_mask:0xf bank_mask:0xf
	v_mov_b32_dpp v189, v97 row_shr:1 row_mask:0xf bank_mask:0xf
	v_mov_b32_dpp v186, v34 row_shr:2 row_mask:0xf bank_mask:0xf
	v_mov_b32_dpp v184, v34 row_shr:1 row_mask:0xf bank_mask:0xf
	v_mov_b32_dpp v182, v98 row_shr:2 row_mask:0xf bank_mask:0xf
	v_mov_b32_dpp v180, v98 row_shr:1 row_mask:0xf bank_mask:0xf
	v_mov_b32_dpp v187, v35 row_shr:2 row_mask:0xf bank_mask:0xf
	v_mov_b32_dpp v185, v35 row_shr:1 row_mask:0xf bank_mask:0xf
	v_mov_b32_dpp v183, v99 row_shr:2 row_mask:0xf bank_mask:0xf
	v_mov_b32_dpp v181, v99 row_shr:1 row_mask:0xf bank_mask:0xf
	s_cmp_lg_u32 s42, 64
	s_cselect_b64 vcc, -1, s[40:41]
	s_and_saveexec_b64 s[0:1], vcc
	s_cbranch_execz .LBB0_627
	s_nop 0
	v_pk_fma_f32 v[194:195], v[146:147], v[194:195], v[158:159]
	v_pk_fma_f32 v[186:187], v[148:149], v[186:187], v[160:161]
	v_pk_fma_f32 v[192:193], v[150:151], v[192:193], v[194:195]
	v_pk_fma_f32 v[184:185], v[152:153], v[184:185], v[186:187]
	v_pk_fma_f32 v[192:193], v[32:33], v[154:155], v[192:193]
	v_pk_fma_f32 v[184:185], v[34:35], v[156:157], v[184:185]
	v_mul_f32_e32 v175, 0x3dd2d3e8, v192
	v_fmaak_f32 v175, v192, v175, 0x40135761
	v_mul_f32_e32 v194, 0x3dd2d3e8, v193
	v_mul_f32_e32 v175, v192, v175
	v_fmaak_f32 v194, v193, v194, 0x40135761
	v_exp_f32_e32 v175, v175
	v_mul_f32_e32 v194, v193, v194
	v_exp_f32_e32 v195, v194
	v_mul_f32_e32 v186, 0x3dd2d3e8, v185
	v_add_f32_e32 v175, 1.0, v175
	v_rcp_f32_e32 v194, v175
	v_add_f32_e32 v175, 1.0, v195
	v_rcp_f32_e32 v195, v175
	v_mul_f32_e32 v175, 0x3dd2d3e8, v184
	v_fmaak_f32 v175, v184, v175, 0x40135761
	v_mul_f32_e32 v175, v184, v175
	v_fmaak_f32 v186, v185, v186, 0x40135761
	s_nop 0
	v_pk_fma_f32 v[190:191], v[130:131], v[190:191], v[142:143]
	v_exp_f32_e32 v175, v175
	v_mul_f32_e32 v186, v185, v186
	v_pk_fma_f32 v[188:189], v[134:135], v[188:189], v[190:191]
	v_pk_fma_f32 v[190:191], v[192:193], v[194:195], v[192:193] neg_lo:[1,0,0] neg_hi:[1,0,0]
	v_exp_f32_e32 v192, v186
	v_pk_fma_f32 v[188:189], v[96:97], v[138:139], v[188:189]
	v_add_f32_e32 v175, 1.0, v175
	v_pk_mul_f32 v[186:187], v[188:189], v[190:191]
	v_rcp_f32_e32 v188, v175
	v_add_f32_e32 v175, 1.0, v192
	v_rcp_f32_e32 v189, v175
	v_pk_fma_f32 v[182:183], v[132:133], v[182:183], v[144:145]
	s_nop 0
	v_pk_fma_f32 v[180:181], v[136:137], v[180:181], v[182:183]
	v_pk_fma_f32 v[182:183], v[184:185], v[188:189], v[184:185] neg_lo:[1,0,0] neg_hi:[1,0,0]
	v_pk_fma_f32 v[180:181], v[98:99], v[140:141], v[180:181]
	s_nop 0
	v_pk_mul_f32 v[180:181], v[180:181], v[182:183]
	v_cvt_pk_bf16_f32 v182, v186, v187
	v_cvt_pk_bf16_f32 v183, v180, v181
	v_mad_i64_i32 v[180:181], s[6:7], v206, s5, v[178:179]
	global_store_dwordx2 v[180:181], v[182:183], off offset:8

.LBB0_629:
	s_or_b64 exec, exec, s[0:1]
	s_cmp_lg_u32 s42, 64
	s_cselect_b64 exec, -1, 0
	s_nop 1
	v_mov_b32_dpp v194, v24 row_ror:2 row_mask:0xf bank_mask:0x1
	v_mov_b32_dpp v192, v24 row_ror:1 row_mask:0xf bank_mask:0x1
	v_mov_b32_dpp v190, v88 row_ror:2 row_mask:0xf bank_mask:0x1
	v_mov_b32_dpp v188, v88 row_ror:1 row_mask:0xf bank_mask:0x1
	v_mov_b32_dpp v195, v25 row_ror:2 row_mask:0xf bank_mask:0x1
	v_mov_b32_dpp v193, v25 row_ror:1 row_mask:0xf bank_mask:0x1
	v_mov_b32_dpp v191, v89 row_ror:2 row_mask:0xf bank_mask:0x1
	v_mov_b32_dpp v189, v89 row_ror:1 row_mask:0xf bank_mask:0x1
	v_mov_b32_dpp v186, v26 row_ror:2 row_mask:0xf bank_mask:0x1
	v_mov_b32_dpp v184, v26 row_ror:1 row_mask:0xf bank_mask:0x1
	v_mov_b32_dpp v182, v90 row_ror:2 row_mask:0xf bank_mask:0x1
	v_mov_b32_dpp v180, v90 row_ror:1 row_mask:0xf bank_mask:0x1
	v_mov_b32_dpp v187, v27 row_ror:2 row_mask:0xf bank_mask:0x1
	v_mov_b32_dpp v185, v27 row_ror:1 row_mask:0xf bank_mask:0x1
	v_mov_b32_dpp v183, v91 row_ror:2 row_mask:0xf bank_mask:0x1
	v_mov_b32_dpp v181, v91 row_ror:1 row_mask:0xf bank_mask:0x1
	s_mov_b64 exec, -1
	s_nop 1
	v_mov_b32_dpp v194, v16 row_shr:2 row_mask:0xf bank_mask:0xf
	v_mov_b32_dpp v192, v16 row_shr:1 row_mask:0xf bank_mask:0xf
	v_mov_b32_dpp v190, v80 row_shr:2 row_mask:0xf bank_mask:0xf
	v_mov_b32_dpp v188, v80 row_shr:1 row_mask:0xf bank_mask:0xf
	v_mov_b32_dpp v195, v17 row_shr:2 row_mask:0xf bank_mask:0xf
	v_mov_b32_dpp v193, v17 row_shr:1 row_mask:0xf bank_mask:0xf
	v_mov_b32_dpp v191, v81 row_shr:2 row_mask:0xf bank_mask:0xf
	v_mov_b32_dpp v189, v81 row_shr:1 row_mask:0xf bank_mask:0xf
	v_mov_b32_dpp v186, v18 row_shr:2 row_mask:0xf bank_mask:0xf
	v_mov_b32_dpp v184, v18 row_shr:1 row_mask:0xf bank_mask:0xf
	v_mov_b32_dpp v182, v82 row_shr:2 row_mask:0xf bank_mask:0xf
	v_mov_b32_dpp v180, v82 row_shr:1 row_mask:0xf bank_mask:0xf
	v_mov_b32_dpp v187, v19 row_shr:2 row_mask:0xf bank_mask:0xf
	v_mov_b32_dpp v185, v19 row_shr:1 row_mask:0xf bank_mask:0xf
	v_mov_b32_dpp v183, v83 row_shr:2 row_mask:0xf bank_mask:0xf
	v_mov_b32_dpp v181, v83 row_shr:1 row_mask:0xf bank_mask:0xf
	s_cmp_lg_u32 s42, 64
	s_cselect_b64 vcc, -1, s[40:41]
	s_and_saveexec_b64 s[0:1], vcc
	s_cbranch_execz .LBB0_631
	s_nop 0
	v_pk_fma_f32 v[194:195], v[146:147], v[194:195], v[158:159]
	v_pk_fma_f32 v[186:187], v[148:149], v[186:187], v[160:161]
	v_pk_fma_f32 v[192:193], v[150:151], v[192:193], v[194:195]
	v_pk_fma_f32 v[184:185], v[152:153], v[184:185], v[186:187]
	v_pk_fma_f32 v[192:193], v[16:17], v[154:155], v[192:193]
	v_pk_fma_f32 v[184:185], v[18:19], v[156:157], v[184:185]
	v_mul_f32_e32 v173, 0x3dd2d3e8, v192
	v_fmaak_f32 v173, v192, v173, 0x40135761
	v_mul_f32_e32 v175, 0x3dd2d3e8, v193
	v_mul_f32_e32 v173, v192, v173
	v_fmaak_f32 v175, v193, v175, 0x40135761
	v_exp_f32_e32 v173, v173
	v_mul_f32_e32 v175, v193, v175
	v_exp_f32_e32 v175, v175
	s_nop 0
	v_pk_fma_f32 v[190:191], v[130:131], v[190:191], v[142:143]
	v_add_f32_e32 v173, 1.0, v173
	v_rcp_f32_e32 v194, v173
	v_add_f32_e32 v173, 1.0, v175
	v_rcp_f32_e32 v195, v173
	v_mul_f32_e32 v173, 0x3dd2d3e8, v184
	v_fmaak_f32 v173, v184, v173, 0x40135761
	v_mul_f32_e32 v175, 0x3dd2d3e8, v185
	v_mul_f32_e32 v173, v184, v173
	v_fmaak_f32 v175, v185, v175, 0x40135761
	v_exp_f32_e32 v173, v173
	v_mul_f32_e32 v175, v185, v175
	v_exp_f32_e32 v175, v175
	v_pk_fma_f32 v[188:189], v[134:135], v[188:189], v[190:191]
	v_pk_fma_f32 v[190:191], v[192:193], v[194:195], v[192:193] neg_lo:[1,0,0] neg_hi:[1,0,0]
	v_pk_fma_f32 v[188:189], v[80:81], v[138:139], v[188:189]
	v_add_f32_e32 v173, 1.0, v173
	v_pk_mul_f32 v[186:187], v[188:189], v[190:191]
	v_rcp_f32_e32 v188, v173
	v_add_f32_e32 v173, 1.0, v175
	v_rcp_f32_e32 v189, v173
	v_pk_fma_f32 v[182:183], v[132:133], v[182:183], v[144:145]
	s_nop 0
	v_pk_fma_f32 v[180:181], v[136:137], v[180:181], v[182:183]
	v_pk_fma_f32 v[182:183], v[184:185], v[188:189], v[184:185] neg_lo:[1,0,0] neg_hi:[1,0,0]
	v_pk_fma_f32 v[180:181], v[82:83], v[140:141], v[180:181]
	s_nop 0
	v_pk_mul_f32 v[180:181], v[180:181], v[182:183]
	v_cvt_pk_bf16_f32 v182, v186, v187
	v_cvt_pk_bf16_f32 v183, v180, v181
	v_mad_i64_i32 v[180:181], s[6:7], v207, s5, v[178:179]
	global_store_dwordx2 v[180:181], v[182:183], off offset:8
.LBB0_631:
	s_or_b64 exec, exec, s[0:1]
	s_cmp_lg_u32 s42, 64
	s_cselect_b64 exec, -1, 0
	s_nop 1
	v_mov_b32_dpp v194, v16 row_ror:2 row_mask:0xf bank_mask:0x1
	v_mov_b32_dpp v192, v16 row_ror:1 row_mask:0xf bank_mask:0x1
	v_mov_b32_dpp v190, v80 row_ror:2 row_mask:0xf bank_mask:0x1
	v_mov_b32_dpp v188, v80 row_ror:1 row_mask:0xf bank_mask:0x1
	v_mov_b32_dpp v195, v17 row_ror:2 row_mask:0xf bank_mask:0x1
	v_mov_b32_dpp v193, v17 row_ror:1 row_mask:0xf bank_mask:0x1
	v_mov_b32_dpp v191, v81 row_ror:2 row_mask:0xf bank_mask:0x1
	v_mov_b32_dpp v189, v81 row_ror:1 row_mask:0xf bank_mask:0x1
	v_mov_b32_dpp v186, v18 row_ror:2 row_mask:0xf bank_mask:0x1
	v_mov_b32_dpp v184, v18 row_ror:1 row_mask:0xf bank_mask:0x1
	v_mov_b32_dpp v182, v82 row_ror:2 row_mask:0xf bank_mask:0x1
	v_mov_b32_dpp v180, v82 row_ror:1 row_mask:0xf bank_mask:0x1
	v_mov_b32_dpp v187, v19 row_ror:2 row_mask:0xf bank_mask:0x1
	v_mov_b32_dpp v185, v19 row_ror:1 row_mask:0xf bank_mask:0x1
	v_mov_b32_dpp v183, v83 row_ror:2 row_mask:0xf bank_mask:0x1
	v_mov_b32_dpp v181, v83 row_ror:1 row_mask:0xf bank_mask:0x1
	s_mov_b64 exec, -1
	s_nop 1
	v_mov_b32_dpp v194, v8 row_shr:2 row_mask:0xf bank_mask:0xf
	v_mov_b32_dpp v192, v8 row_shr:1 row_mask:0xf bank_mask:0xf
	v_mov_b32_dpp v190, v72 row_shr:2 row_mask:0xf bank_mask:0xf
	v_mov_b32_dpp v188, v72 row_shr:1 row_mask:0xf bank_mask:0xf
	v_mov_b32_dpp v195, v9 row_shr:2 row_mask:0xf bank_mask:0xf
	v_mov_b32_dpp v193, v9 row_shr:1 row_mask:0xf bank_mask:0xf
	v_mov_b32_dpp v191, v73 row_shr:2 row_mask:0xf bank_mask:0xf
	v_mov_b32_dpp v189, v73 row_shr:1 row_mask:0xf bank_mask:0xf
	v_mov_b32_dpp v186, v10 row_shr:2 row_mask:0xf bank_mask:0xf
	v_mov_b32_dpp v184, v10 row_shr:1 row_mask:0xf bank_mask:0xf
	v_mov_b32_dpp v182, v74 row_shr:2 row_mask:0xf bank_mask:0xf
	v_mov_b32_dpp v180, v74 row_shr:1 row_mask:0xf bank_mask:0xf
	v_mov_b32_dpp v187, v11 row_shr:2 row_mask:0xf bank_mask:0xf
	v_mov_b32_dpp v185, v11 row_shr:1 row_mask:0xf bank_mask:0xf
	v_mov_b32_dpp v183, v75 row_shr:2 row_mask:0xf bank_mask:0xf
	v_mov_b32_dpp v181, v75 row_shr:1 row_mask:0xf bank_mask:0xf
	s_cmp_lg_u32 s42, 64
	s_cselect_b64 vcc, -1, s[40:41]
	s_and_saveexec_b64 s[0:1], vcc
	s_cbranch_execz .LBB0_633
	s_nop 0
	v_pk_fma_f32 v[194:195], v[146:147], v[194:195], v[158:159]
	v_pk_fma_f32 v[186:187], v[148:149], v[186:187], v[160:161]
	v_pk_fma_f32 v[192:193], v[150:151], v[192:193], v[194:195]
	v_pk_fma_f32 v[184:185], v[152:153], v[184:185], v[186:187]
	v_pk_fma_f32 v[192:193], v[8:9], v[154:155], v[192:193]
	v_pk_fma_f32 v[184:185], v[10:11], v[156:157], v[184:185]
	v_mul_f32_e32 v173, 0x3dd2d3e8, v192
	v_fmaak_f32 v173, v192, v173, 0x40135761
	v_mul_f32_e32 v175, 0x3dd2d3e8, v193
	v_mul_f32_e32 v173, v192, v173
	v_fmaak_f32 v175, v193, v175, 0x40135761
	v_exp_f32_e32 v173, v173
	v_mul_f32_e32 v175, v193, v175
	v_exp_f32_e32 v175, v175
	s_nop 0
	v_pk_fma_f32 v[190:191], v[130:131], v[190:191], v[142:143]
	v_add_f32_e32 v173, 1.0, v173
	v_rcp_f32_e32 v194, v173
	v_add_f32_e32 v173, 1.0, v175
	v_rcp_f32_e32 v195, v173
	v_mul_f32_e32 v173, 0x3dd2d3e8, v184
	v_fmaak_f32 v173, v184, v173, 0x40135761
	v_mul_f32_e32 v175, 0x3dd2d3e8, v185
	v_mul_f32_e32 v173, v184, v173
	v_fmaak_f32 v175, v185, v175, 0x40135761
	v_exp_f32_e32 v173, v173
	v_mul_f32_e32 v175, v185, v175
	v_exp_f32_e32 v175, v175
	v_pk_fma_f32 v[188:189], v[134:135], v[188:189], v[190:191]
	v_pk_fma_f32 v[190:191], v[192:193], v[194:195], v[192:193] neg_lo:[1,0,0] neg_hi:[1,0,0]
	v_pk_fma_f32 v[188:189], v[72:73], v[138:139], v[188:189]
	v_add_f32_e32 v173, 1.0, v173
	v_pk_mul_f32 v[186:187], v[188:189], v[190:191]
	v_rcp_f32_e32 v188, v173
	v_add_f32_e32 v173, 1.0, v175
	v_rcp_f32_e32 v189, v173
	v_pk_fma_f32 v[182:183], v[132:133], v[182:183], v[144:145]
	s_nop 0
	v_pk_fma_f32 v[180:181], v[136:137], v[180:181], v[182:183]
	v_pk_fma_f32 v[182:183], v[184:185], v[188:189], v[184:185] neg_lo:[1,0,0] neg_hi:[1,0,0]
	v_pk_fma_f32 v[180:181], v[74:75], v[140:141], v[180:181]
	s_nop 0
	v_pk_mul_f32 v[180:181], v[180:181], v[182:183]
	v_cvt_pk_bf16_f32 v182, v186, v187
	v_cvt_pk_bf16_f32 v183, v180, v181
	v_mad_i64_i32 v[180:181], s[6:7], v208, s5, v[178:179]
	global_store_dwordx2 v[180:181], v[182:183], off offset:8
.LBB0_633:
	s_or_b64 exec, exec, s[0:1]
	s_cmp_lg_u32 s42, 64
	s_cselect_b64 exec, -1, 0
	s_nop 1
	v_mov_b32_dpp v194, v8 row_ror:2 row_mask:0xf bank_mask:0x1
	v_mov_b32_dpp v192, v8 row_ror:1 row_mask:0xf bank_mask:0x1
	v_mov_b32_dpp v190, v72 row_ror:2 row_mask:0xf bank_mask:0x1
	v_mov_b32_dpp v188, v72 row_ror:1 row_mask:0xf bank_mask:0x1
	v_mov_b32_dpp v195, v9 row_ror:2 row_mask:0xf bank_mask:0x1
	v_mov_b32_dpp v193, v9 row_ror:1 row_mask:0xf bank_mask:0x1
	v_mov_b32_dpp v191, v73 row_ror:2 row_mask:0xf bank_mask:0x1
	v_mov_b32_dpp v189, v73 row_ror:1 row_mask:0xf bank_mask:0x1
	v_mov_b32_dpp v186, v10 row_ror:2 row_mask:0xf bank_mask:0x1
	v_mov_b32_dpp v184, v10 row_ror:1 row_mask:0xf bank_mask:0x1
	v_mov_b32_dpp v182, v74 row_ror:2 row_mask:0xf bank_mask:0x1
	v_mov_b32_dpp v180, v74 row_ror:1 row_mask:0xf bank_mask:0x1
	v_mov_b32_dpp v187, v11 row_ror:2 row_mask:0xf bank_mask:0x1
	v_mov_b32_dpp v185, v11 row_ror:1 row_mask:0xf bank_mask:0x1
	v_mov_b32_dpp v183, v75 row_ror:2 row_mask:0xf bank_mask:0x1
	v_mov_b32_dpp v181, v75 row_ror:1 row_mask:0xf bank_mask:0x1
	s_mov_b64 exec, -1
	s_nop 1
	v_mov_b32_dpp v194, v0 row_shr:2 row_mask:0xf bank_mask:0xf
	v_mov_b32_dpp v192, v0 row_shr:1 row_mask:0xf bank_mask:0xf
	v_mov_b32_dpp v190, v60 row_shr:2 row_mask:0xf bank_mask:0xf
	v_mov_b32_dpp v188, v60 row_shr:1 row_mask:0xf bank_mask:0xf
	v_mov_b32_dpp v195, v1 row_shr:2 row_mask:0xf bank_mask:0xf
	v_mov_b32_dpp v193, v1 row_shr:1 row_mask:0xf bank_mask:0xf
	v_mov_b32_dpp v191, v61 row_shr:2 row_mask:0xf bank_mask:0xf
	v_mov_b32_dpp v189, v61 row_shr:1 row_mask:0xf bank_mask:0xf
	v_mov_b32_dpp v186, v2 row_shr:2 row_mask:0xf bank_mask:0xf
	v_mov_b32_dpp v184, v2 row_shr:1 row_mask:0xf bank_mask:0xf
	v_mov_b32_dpp v182, v62 row_shr:2 row_mask:0xf bank_mask:0xf
	v_mov_b32_dpp v180, v62 row_shr:1 row_mask:0xf bank_mask:0xf
	v_mov_b32_dpp v187, v3 row_shr:2 row_mask:0xf bank_mask:0xf
	v_mov_b32_dpp v185, v3 row_shr:1 row_mask:0xf bank_mask:0xf
	v_mov_b32_dpp v183, v63 row_shr:2 row_mask:0xf bank_mask:0xf
	v_mov_b32_dpp v181, v63 row_shr:1 row_mask:0xf bank_mask:0xf
	s_cmp_lg_u32 s42, 64
	s_cselect_b64 vcc, -1, s[40:41]
	s_and_saveexec_b64 s[0:1], vcc
	s_cbranch_execz .LBB0_635
	s_nop 0
	v_pk_fma_f32 v[146:147], v[146:147], v[194:195], v[158:159]
	s_nop 0
	v_pk_fma_f32 v[130:131], v[130:131], v[190:191], v[142:143]
	v_pk_fma_f32 v[146:147], v[150:151], v[192:193], v[146:147]
	v_pk_fma_f32 v[130:131], v[134:135], v[188:189], v[130:131]
	v_pk_fma_f32 v[146:147], v[0:1], v[154:155], v[146:147]
	v_pk_fma_f32 v[130:131], v[60:61], v[138:139], v[130:131]
	v_mul_f32_e32 v150, 0x3dd2d3e8, v146
	v_mul_f32_e32 v151, 0x3dd2d3e8, v147
	v_fmaak_f32 v150, v146, v150, 0x40135761
	v_fmaak_f32 v151, v147, v151, 0x40135761
	v_mul_f32_e32 v150, v146, v150
	v_mul_f32_e32 v151, v147, v151
	v_exp_f32_e32 v150, v150
	v_exp_f32_e32 v151, v151
	v_pk_fma_f32 v[138:139], v[148:149], v[186:187], v[160:161]
	v_pk_fma_f32 v[132:133], v[132:133], v[182:183], v[144:145]
	v_pk_fma_f32 v[138:139], v[152:153], v[184:185], v[138:139]
	v_add_f32_e32 v150, 1.0, v150
	v_pk_fma_f32 v[138:139], v[2:3], v[156:157], v[138:139]
	v_add_f32_e32 v151, 1.0, v151
	v_mul_f32_e32 v142, 0x3dd2d3e8, v138
	v_mul_f32_e32 v143, 0x3dd2d3e8, v139
	v_fmaak_f32 v142, v138, v142, 0x40135761
	v_fmaak_f32 v143, v139, v143, 0x40135761
	v_rcp_f32_e32 v150, v150
	v_rcp_f32_e32 v151, v151
	v_mul_f32_e32 v142, v138, v142
	v_mul_f32_e32 v143, v139, v143
	v_exp_f32_e32 v142, v142
	v_exp_f32_e32 v143, v143
	v_pk_fma_f32 v[134:135], v[146:147], v[150:151], v[146:147] neg_lo:[1,0,0] neg_hi:[1,0,0]
	v_pk_fma_f32 v[132:133], v[136:137], v[180:181], v[132:133]
	v_pk_mul_f32 v[130:131], v[130:131], v[134:135]
	v_add_f32_e32 v134, 1.0, v142
	v_add_f32_e32 v135, 1.0, v143
	v_rcp_f32_e32 v134, v134
	v_rcp_f32_e32 v135, v135
	v_pk_fma_f32 v[132:133], v[62:63], v[140:141], v[132:133]
	v_cvt_pk_bf16_f32 v130, v130, v131
	v_pk_fma_f32 v[134:135], v[138:139], v[134:135], v[138:139] neg_lo:[1,0,0] neg_hi:[1,0,0]
	s_nop 0
	v_pk_mul_f32 v[132:133], v[132:133], v[134:135]
	s_nop 0
	v_cvt_pk_bf16_f32 v131, v132, v133
	v_mad_i64_i32 v[132:133], s[6:7], v209, s5, v[178:179]
	global_store_dwordx2 v[132:133], v[130:131], off offset:8
